# phase 1: half of the PLE workgroups convert their layer-1 weight tiles before their GEMM tiles, the rest after, so the conversion bursts no longer all coincide at the phase end
# speedup vs baseline: 1.0160x; 1.0055x over previous
.Lprio_skip:
	s_mov_b32 s98, 0
	s_nop 0
	v_writelane_b32 v255, s98, 44
	v_writelane_b32 v255, s4, 0
	s_nop 1
	v_writelane_b32 v255, s5, 1
	v_writelane_b32 v255, s6, 2
	v_writelane_b32 v255, s7, 3
	v_writelane_b32 v255, s8, 4
	v_writelane_b32 v255, s9, 5
	v_writelane_b32 v255, s10, 6
	v_writelane_b32 v255, s11, 7
	v_writelane_b32 v255, s2, 8
	v_cmp_eq_u32_e64 s[4:5], 0, v0
	s_nop 0
	v_writelane_b32 v255, s3, 9
	s_mov_b64 s[2:3], exec
	v_writelane_b32 v255, s4, 10
	s_nop 1
	v_writelane_b32 v255, s5, 11
	s_and_b64 s[4:5], s[2:3], s[4:5]
	s_mov_b64 exec, s[4:5]
	s_cbranch_execz .LBB0_2
	s_add_i32 s4, 0, 0x20000
	v_mov_b32_e32 v1, 0
	v_mov_b32_e32 v2, s4
	s_add_i32 s4, 0, 0x20004
	ds_write_b32 v2, v1
	v_mov_b32_e32 v2, s4
	ds_write_b32 v2, v1

.LBB0_241:
	s_cmp_lt_i32 s94, 2
	s_cselect_b64 s[0:1], -1, 0
	s_and_b64 s[2:3], s[0:1], s[2:3]
	v_writelane_b32 v255, s66, 29
	s_andn2_b64 vcc, exec, s[2:3]
	s_nop 0
	v_writelane_b32 v255, s67, 30
	s_cbranch_vccnz .LBB0_699
	s_bfe_u32 s98, s97, 0x10003
	s_cmpk_lt_u32 s97, 0x40
	s_cselect_b32 s98, 0, s98
	s_nop 0
	v_writelane_b32 v255, s98, 44
	s_nop 3
.Lp1_top:
	v_readlane_b32 s98, v255, 44
	s_nop 3
	s_cmp_eq_u32 s98, 1
	s_cbranch_scc1 .Lp1_wcfirst
	s_cmpk_lt_i32 s97, 0x540
	v_readfirstlane_b32 s27, v0
	s_movk_i32 s2, 0x800
	s_cselect_b64 s[4:5], -1, 0
	s_cmpk_gt_i32 s97, 0x53f
	s_cbranch_scc1 .LBB0_244
	s_ashr_i32 s3, s97, 31
	s_lshr_b32 s3, s3, 29
	s_add_i32 s3, s97, s3
	s_ashr_i32 s6, s3, 3
	s_and_b32 s3, s3, -8
	s_sub_i32 s3, s97, s3
	s_cmp_lt_i32 s3, 0
	s_movk_i32 s7, 0xa9
	s_cselect_b32 s7, s7, 0xa8
	s_mul_i32 s3, s7, s3
	s_add_i32 s3, s3, s6
	s_mul_hi_i32 s6, s3, 0x30c30c31
	s_lshr_b32 s7, s6, 31
	s_ashr_i32 s6, s6, 5
	s_add_i32 s6, s6, s7
	s_lshl_b32 s7, s6, 3
	s_mulk_i32 s6, 0xa8
	s_sub_i32 s3, s3, s6
	s_sext_i32_i16 s6, s3
	s_bfe_u32 s6, s6, 0x3001c
	s_add_i32 s6, s3, s6
	s_sext_i32_i16 s8, s6
	s_and_b32 s6, s6, 0xfff8
	s_sub_i32 s3, s3, s6
	s_sext_i32_i16 s3, s3
	s_add_i32 s6, s7, s3
	s_ashr_i32 s29, s8, 3

.LBB0_521:
	s_barrier
	s_branch .LBB0_522
.Lp1_wcfirst:
	s_add_u32 s8, s92, 0x2500000
	s_addc_u32 s9, s93, 0
	s_sub_i32 s40, s96, 64
	s_sub_i32 s41, s97, 64
	v_lshrrev_b32_e32 v1, 3, v0
.LBB0_522:
	v_readlane_b32 s98, v255, 44
	s_nop 3
	s_cmp_eq_u32 s98, 2
	s_cbranch_scc1 .LBB0_699
	s_movk_i32 s98, 0x940
	s_mov_b32 s99, 0
	s_cmpk_lt_i32 s41, 0x80
	s_cbranch_scc1 .Lwc_go
	s_add_i32 s99, s41, 0x400
	s_branch .Lwc_go

.LBB0_699:
	v_readlane_b32 s98, v255, 44
	s_nop 3
	s_cmp_eq_u32 s98, 1
	s_cbranch_scc0 .Lp1_done
	s_mov_b32 s98, 2
	s_nop 0
	v_writelane_b32 v255, s98, 44
	s_waitcnt vmcnt(0) lgkmcnt(0)
	s_barrier
	s_branch .Lp1_top
